# in-proj / gate-up epilogues: row-scale butterfly (lane^16, lane^32) via v_permlane16_swap / v_permlane32_swap on a register copy instead of ds_bpermute
# speedup vs baseline: 1.0031x; 1.0026x over previous
.Lp2_rr_join:
	v_mov_b32_e32 v184, v203
	v_mov_b32_e32 v185, v204
	v_mov_b32_e32 v203, v205
	v_mov_b32_e32 v190, v207
	v_mov_b32_e32 v191, v208
	v_mov_b32_e32 v207, v209
	v_pk_add_f32 v[184:185], v[184:185], v[202:203]
	v_pk_add_f32 v[190:191], v[190:191], v[206:207]
	v_cndmask_b32_e32 v180, v239, v180, vcc
	v_mov_b32_e32 v202, v190
	v_mov_b32_e32 v203, v184
	v_mov_b32_e32 v184, v191
	v_lshlrev_b32_e32 v189, 2, v180
	v_pk_add_f32 v[184:185], v[202:203], v[184:185]
	v_mov_b32_e32 v191, v185
	v_mov_b32_e32 v190, v184
	v_xor_b32_e32 v180, 32, v239
	v_cmp_lt_i32_e32 vcc, v180, v182
	s_waitcnt lgkmcnt(0)
	s_nop 1
	v_permlane16_swap_b32 v190, v184
	v_permlane16_swap_b32 v191, v185
	v_pk_add_f32 v[184:185], v[184:185], v[190:191]
	v_cndmask_b32_e32 v180, v239, v180, vcc
	v_lshlrev_b32_e32 v188, 2, v180
	v_mov_b32_e32 v191, v185
	v_mov_b32_e32 v190, v184
	s_waitcnt lgkmcnt(0)
	s_nop 1
	v_permlane32_swap_b32 v190, v184
	v_permlane32_swap_b32 v191, v185
	v_pk_add_f32 v[190:191], v[184:185], v[190:191]
	v_mov_b64_e32 v[184:185], s[80:81]
	v_pk_fma_f32 v[190:191], v[190:191], s[78:79], v[184:185] op_sel_hi:[1,0,0]
	s_nop 0
	v_mul_f32_e32 v180, 0x4b800000, v191
	v_cmp_gt_f32_e64 s[8:9], s66, v191
	v_cmp_gt_f32_e32 vcc, s66, v190
	s_nop 0
	v_cndmask_b32_e64 v180, v191, v180, s[8:9]
	v_rsq_f32_e32 v180, v180
	v_mov_b32_e32 v191, v150
	v_mov_b32_e32 v150, v145
	v_mov_b32_e32 v145, v147
	v_mul_f32_e32 v182, 0x45800000, v180
	v_cndmask_b32_e64 v182, v180, v182, s[8:9]
	v_mul_f32_e32 v180, 0x4b800000, v190
	v_cndmask_b32_e32 v180, v190, v180, vcc
	v_rsq_f32_e32 v180, v180
	s_nop 0
	v_mul_f32_e32 v190, 0x45800000, v180
	v_cndmask_b32_e32 v180, v180, v190, vcc
	v_mov_b32_e32 v190, v149
	v_mov_b32_e32 v149, v151
	v_mov_b32_e32 v151, v146
	v_pk_add_f32 v[148:149], v[190:191], v[148:149]
	v_pk_add_f32 v[144:145], v[150:151], v[144:145]
	v_mov_b32_e32 v147, v148
	v_mov_b32_e32 v146, v144
	v_mov_b32_e32 v148, v145
	v_pk_add_f32 v[144:145], v[146:147], v[148:149]
	v_mov_b32_e32 v147, v145
	v_mov_b32_e32 v146, v144
	v_mov_b32_e32 v148, v141
	v_mov_b32_e32 v149, v142
	v_mov_b32_e32 v141, v143
	v_mov_b32_e32 v142, v137
	v_mov_b32_e32 v143, v138
	v_mov_b32_e32 v137, v139
	v_pk_add_f32 v[140:141], v[148:149], v[140:141]
	v_pk_add_f32 v[136:137], v[142:143], v[136:137]
	s_waitcnt lgkmcnt(0)
	s_nop 1
	v_permlane16_swap_b32 v146, v144
	v_permlane16_swap_b32 v147, v145
	v_pk_add_f32 v[144:145], v[144:145], v[146:147]
	v_mov_b32_e32 v138, v136
	v_mov_b32_e32 v139, v140
	v_mov_b32_e32 v140, v137
	v_mov_b32_e32 v147, v145
	v_mov_b32_e32 v146, v144
	v_pk_add_f32 v[136:137], v[138:139], v[140:141]
	v_mov_b32_e32 v139, v137
	v_mov_b32_e32 v138, v136
	v_mov_b32_e32 v140, v133
	v_mov_b32_e32 v141, v134
	v_mov_b32_e32 v133, v135
	v_mov_b32_e32 v134, v129
	v_mov_b32_e32 v135, v130
	v_mov_b32_e32 v129, v131
	s_waitcnt lgkmcnt(2)
	s_nop 1
	v_permlane32_swap_b32 v146, v144
	v_permlane32_swap_b32 v147, v145
	v_pk_add_f32 v[144:145], v[144:145], v[146:147]
	v_pk_add_f32 v[132:133], v[140:141], v[132:133]
	v_pk_add_f32 v[128:129], v[134:135], v[128:129]
	v_pk_fma_f32 v[144:145], v[144:145], s[78:79], v[184:185] op_sel_hi:[1,0,0]
	s_waitcnt lgkmcnt(0)
	s_nop 1
	v_permlane16_swap_b32 v138, v136
	v_permlane16_swap_b32 v139, v137
	v_pk_add_f32 v[136:137], v[136:137], v[138:139]
	v_mov_b32_e32 v130, v128
	v_mov_b32_e32 v131, v132
	v_mov_b32_e32 v132, v129
	v_mul_f32_e32 v146, 0x4b800000, v145
	v_cmp_gt_f32_e64 s[8:9], s66, v145
	v_mov_b32_e32 v139, v137
	v_mov_b32_e32 v138, v136
	v_pk_add_f32 v[128:129], v[130:131], v[132:133]
	v_cndmask_b32_e64 v145, v145, v146, s[8:9]
	v_mov_b32_e32 v131, v129
	v_mov_b32_e32 v130, v128
	v_rsq_f32_e32 v145, v145
	s_waitcnt lgkmcnt(2)
	s_nop 1
	v_permlane32_swap_b32 v138, v136
	v_permlane32_swap_b32 v139, v137
	v_pk_add_f32 v[136:137], v[136:137], v[138:139]
	v_cmp_gt_f32_e32 vcc, s66, v144
	v_pk_fma_f32 v[136:137], v[136:137], s[78:79], v[184:185] op_sel_hi:[1,0,0]
	v_mul_f32_e32 v146, 0x45800000, v145
	s_waitcnt lgkmcnt(0)
	s_nop 1
	v_permlane16_swap_b32 v130, v128
	v_permlane16_swap_b32 v131, v129
	v_pk_add_f32 v[128:129], v[128:129], v[130:131]
	v_cndmask_b32_e64 v146, v145, v146, s[8:9]
	v_mul_f32_e32 v145, 0x4b800000, v144
	v_mul_f32_e32 v138, 0x4b800000, v137
	v_cmp_gt_f32_e64 s[8:9], s66, v137
	v_mov_b32_e32 v131, v129
	v_mov_b32_e32 v130, v128
	v_cndmask_b32_e32 v144, v144, v145, vcc
	v_cndmask_b32_e64 v137, v137, v138, s[8:9]
	v_rsq_f32_e32 v144, v144
	v_rsq_f32_e32 v137, v137
	s_waitcnt lgkmcnt(0)
	s_nop 1
	v_permlane32_swap_b32 v130, v128
	v_permlane32_swap_b32 v131, v129
	v_pk_add_f32 v[128:129], v[128:129], v[130:131]
	v_mul_f32_e32 v145, 0x45800000, v144
	v_mul_f32_e32 v138, 0x45800000, v137
	v_pk_fma_f32 v[128:129], v[128:129], s[78:79], v[184:185] op_sel_hi:[1,0,0]
	v_cndmask_b32_e32 v144, v144, v145, vcc
	v_cmp_gt_f32_e32 vcc, s66, v136
	v_cndmask_b32_e64 v138, v137, v138, s[8:9]
	v_mul_f32_e32 v137, 0x4b800000, v136
	v_mul_f32_e32 v130, 0x4b800000, v129
	v_cmp_gt_f32_e64 s[8:9], s66, v129
	v_cndmask_b32_e32 v136, v136, v137, vcc
	v_rsq_f32_e32 v136, v136
	v_cndmask_b32_e64 v129, v129, v130, s[8:9]
	v_rsq_f32_e32 v129, v129
	v_mul_f32_e32 v137, 0x45800000, v136
	v_cndmask_b32_e32 v136, v136, v137, vcc
	v_mul_f32_e32 v130, 0x45800000, v129
	v_cmp_gt_f32_e32 vcc, s66, v128
	v_cndmask_b32_e64 v142, v129, v130, s[8:9]
	v_mul_f32_e32 v129, 0x4b800000, v128
	v_cndmask_b32_e32 v128, v128, v129, vcc
	v_rsq_f32_e32 v128, v128
	s_mov_b64 s[8:9], -1
	v_mul_f32_e32 v129, 0x45800000, v128
	v_cndmask_b32_e32 v140, v128, v129, vcc
	s_cbranch_scc1 .LBB0_264
	s_andn2_b64 vcc, exec, s[8:9]
	s_cbranch_vccz .LBB0_459

.Lp8_rr_join:
	v_mov_b32_e32 v186, v203
	v_mov_b32_e32 v187, v204
	v_mov_b32_e32 v203, v205
	v_mov_b32_e32 v190, v207
	v_mov_b32_e32 v191, v208
	v_mov_b32_e32 v207, v209
	v_pk_add_f32 v[186:187], v[186:187], v[202:203]
	v_pk_add_f32 v[190:191], v[190:191], v[206:207]
	v_mov_b32_e32 v203, v186
	v_mov_b32_e32 v202, v190
	v_mov_b32_e32 v186, v191
	v_pk_add_f32 v[186:187], v[202:203], v[186:187]
	v_mov_b32_e32 v191, v187
	v_mov_b32_e32 v190, v186
	v_cndmask_b32_e32 v165, v239, v165, vcc
	v_lshlrev_b32_e32 v165, 2, v165
	s_waitcnt lgkmcnt(0)
	s_nop 1
	v_permlane16_swap_b32 v190, v186
	v_permlane16_swap_b32 v191, v187
	v_pk_add_f32 v[186:187], v[186:187], v[190:191]
	v_mov_b32_e32 v191, v187
	v_mov_b32_e32 v190, v186
	s_waitcnt lgkmcnt(0)
	s_nop 1
	v_permlane32_swap_b32 v190, v186
	v_permlane32_swap_b32 v191, v187
	v_pk_add_f32 v[190:191], v[186:187], v[190:191]
	v_mov_b64_e32 v[186:187], s[80:81]
	v_pk_fma_f32 v[190:191], v[190:191], s[78:79], v[186:187] op_sel_hi:[1,0,0]
	s_nop 0
	v_mul_f32_e32 v169, 0x4b800000, v191
	v_cmp_gt_f32_e64 s[8:9], s66, v191
	v_cmp_gt_f32_e32 vcc, s66, v190
	s_nop 0
	v_cndmask_b32_e64 v169, v191, v169, s[8:9]
	v_rsq_f32_e32 v169, v169
	v_mov_b32_e32 v191, v150
	v_mov_b32_e32 v150, v145
	v_mov_b32_e32 v145, v147
	v_mul_f32_e32 v171, 0x45800000, v169
	v_cndmask_b32_e64 v184, v169, v171, s[8:9]
	v_mul_f32_e32 v169, 0x4b800000, v190
	v_cndmask_b32_e32 v169, v190, v169, vcc
	v_mov_b32_e32 v190, v149
	v_mov_b32_e32 v149, v151
	v_mov_b32_e32 v151, v146
	v_pk_add_f32 v[148:149], v[190:191], v[148:149]
	v_pk_add_f32 v[144:145], v[150:151], v[144:145]
	v_mov_b32_e32 v147, v148
	v_mov_b32_e32 v146, v144
	v_mov_b32_e32 v148, v145
	v_pk_add_f32 v[144:145], v[146:147], v[148:149]
	v_mov_b32_e32 v147, v145
	v_mov_b32_e32 v146, v144
	v_mov_b32_e32 v148, v141
	v_mov_b32_e32 v149, v142
	v_mov_b32_e32 v141, v143
	v_mov_b32_e32 v142, v137
	v_mov_b32_e32 v143, v138
	v_mov_b32_e32 v137, v139
	v_pk_add_f32 v[140:141], v[148:149], v[140:141]
	v_pk_add_f32 v[136:137], v[142:143], v[136:137]
	s_waitcnt lgkmcnt(0)
	s_nop 1
	v_permlane16_swap_b32 v146, v144
	v_permlane16_swap_b32 v147, v145
	v_pk_add_f32 v[144:145], v[144:145], v[146:147]
	v_mov_b32_e32 v138, v136
	v_mov_b32_e32 v139, v140
	v_mov_b32_e32 v140, v137
	v_mov_b32_e32 v147, v145
	v_mov_b32_e32 v146, v144
	v_pk_add_f32 v[136:137], v[138:139], v[140:141]
	v_mov_b32_e32 v139, v137
	v_mov_b32_e32 v138, v136
	v_mov_b32_e32 v140, v133
	v_mov_b32_e32 v141, v134
	v_mov_b32_e32 v133, v135
	v_mov_b32_e32 v134, v129
	v_mov_b32_e32 v135, v130
	v_mov_b32_e32 v129, v131
	s_waitcnt lgkmcnt(2)
	s_nop 1
	v_permlane32_swap_b32 v146, v144
	v_permlane32_swap_b32 v147, v145
	v_pk_add_f32 v[144:145], v[144:145], v[146:147]
	v_pk_add_f32 v[132:133], v[140:141], v[132:133]
	v_pk_add_f32 v[128:129], v[134:135], v[128:129]
	v_pk_fma_f32 v[144:145], v[144:145], s[78:79], v[186:187] op_sel_hi:[1,0,0]
	s_waitcnt lgkmcnt(0)
	s_nop 1
	v_permlane16_swap_b32 v138, v136
	v_permlane16_swap_b32 v139, v137
	v_pk_add_f32 v[136:137], v[136:137], v[138:139]
	v_mov_b32_e32 v130, v128
	v_mov_b32_e32 v131, v132
	v_mov_b32_e32 v132, v129
	v_mul_f32_e32 v146, 0x4b800000, v145
	v_cmp_gt_f32_e64 s[8:9], s66, v145
	v_mov_b32_e32 v139, v137
	v_mov_b32_e32 v138, v136
	v_pk_add_f32 v[128:129], v[130:131], v[132:133]
	v_cndmask_b32_e64 v145, v145, v146, s[8:9]
	v_mov_b32_e32 v131, v129
	v_mov_b32_e32 v130, v128
	v_rsq_f32_e32 v169, v169
	v_rsq_f32_e32 v145, v145
	s_waitcnt lgkmcnt(2)
	s_nop 1
	v_permlane32_swap_b32 v138, v136
	v_permlane32_swap_b32 v139, v137
	v_pk_add_f32 v[136:137], v[136:137], v[138:139]
	v_pk_mul_f32 v[124:125], v[124:125], v[184:185] op_sel_hi:[1,0]
	v_mul_f32_e32 v171, 0x45800000, v169
	v_mul_f32_e32 v146, 0x45800000, v145
	v_pk_fma_f32 v[136:137], v[136:137], s[78:79], v[186:187] op_sel_hi:[1,0,0]
	s_waitcnt lgkmcnt(0)
	s_nop 1
	v_permlane16_swap_b32 v130, v128
	v_permlane16_swap_b32 v131, v129
	v_pk_add_f32 v[128:129], v[128:129], v[130:131]
	v_cndmask_b32_e32 v182, v169, v171, vcc
	v_cmp_gt_f32_e32 vcc, s66, v144
	v_cndmask_b32_e64 v146, v145, v146, s[8:9]
	v_mul_f32_e32 v145, 0x4b800000, v144
	v_mul_f32_e32 v138, 0x4b800000, v137
	v_cmp_gt_f32_e64 s[8:9], s66, v137
	v_mov_b32_e32 v131, v129
	v_mov_b32_e32 v130, v128
	v_cndmask_b32_e32 v144, v144, v145, vcc
	v_cndmask_b32_e64 v137, v137, v138, s[8:9]
	v_rsq_f32_e32 v144, v144
	v_rsq_f32_e32 v137, v137
	s_waitcnt lgkmcnt(0)
	s_nop 1
	v_permlane32_swap_b32 v130, v128
	v_permlane32_swap_b32 v131, v129
	v_pk_add_f32 v[128:129], v[128:129], v[130:131]
	v_pk_mul_f32 v[120:121], v[120:121], v[184:185] op_sel_hi:[1,0]
	v_mul_f32_e32 v145, 0x45800000, v144
	v_mul_f32_e32 v138, 0x45800000, v137
	v_pk_fma_f32 v[128:129], v[128:129], s[78:79], v[186:187] op_sel_hi:[1,0,0]
	v_cndmask_b32_e32 v144, v144, v145, vcc
	v_cmp_gt_f32_e32 vcc, s66, v136
	v_cndmask_b32_e64 v138, v137, v138, s[8:9]
	v_mul_f32_e32 v137, 0x4b800000, v136
	v_mul_f32_e32 v130, 0x4b800000, v129
	v_cmp_gt_f32_e64 s[8:9], s66, v129
	v_cndmask_b32_e32 v136, v136, v137, vcc
	v_rsq_f32_e32 v136, v136
	v_cndmask_b32_e64 v129, v129, v130, s[8:9]
	v_rsq_f32_e32 v129, v129
	v_pk_mul_f32 v[122:123], v[122:123], v[184:185] op_sel_hi:[1,0]
	v_mul_f32_e32 v137, 0x45800000, v136
	v_cndmask_b32_e32 v136, v136, v137, vcc
	v_mul_f32_e32 v130, 0x45800000, v129
	v_cmp_gt_f32_e32 vcc, s66, v128
	v_cndmask_b32_e64 v130, v129, v130, s[8:9]
	v_mul_f32_e32 v129, 0x4b800000, v128
	v_cndmask_b32_e32 v128, v128, v129, vcc
	v_rsq_f32_e32 v128, v128
	v_pk_mul_f32 v[116:117], v[116:117], v[184:185] op_sel_hi:[1,0]
	v_pk_mul_f32 v[112:113], v[112:113], v[184:185] op_sel_hi:[1,0]
	v_pk_mul_f32 v[114:115], v[114:115], v[184:185] op_sel_hi:[1,0]
	v_mul_f32_e32 v129, 0x45800000, v128
	v_cndmask_b32_e32 v128, v128, v129, vcc
	v_mul_f32_e32 v129, 0xbfb8aa3b, v124
	v_exp_f32_e32 v129, v129
	v_pk_mul_f32 v[108:109], v[108:109], v[182:183] op_sel_hi:[1,0]
	v_pk_mul_f32 v[104:105], v[104:105], v[182:183] op_sel_hi:[1,0]
	v_pk_mul_f32 v[106:107], v[106:107], v[182:183] op_sel_hi:[1,0]
	v_add_f32_e32 v129, 1.0, v129
	v_rcp_f32_e32 v132, v129
	v_mul_f32_e32 v129, 0xbfb8aa3b, v125
	v_exp_f32_e32 v129, v129
	v_pk_mul_f32 v[100:101], v[100:101], v[182:183] op_sel_hi:[1,0]
	v_pk_mul_f32 v[96:97], v[96:97], v[182:183] op_sel_hi:[1,0]
	v_pk_mul_f32 v[98:99], v[98:99], v[182:183] op_sel_hi:[1,0]
	v_add_f32_e32 v129, 1.0, v129
	v_rcp_f32_e32 v133, v129
	v_pk_mul_f32 v[92:93], v[92:93], v[146:147] op_sel_hi:[1,0]
	v_pk_mul_f32 v[88:89], v[88:89], v[146:147] op_sel_hi:[1,0]
	v_pk_mul_f32 v[90:91], v[90:91], v[146:147] op_sel_hi:[1,0]
	v_pk_mul_f32 v[124:125], v[124:125], v[132:133]
	v_pk_mul_f32 v[84:85], v[84:85], v[146:147] op_sel_hi:[1,0]
	v_pk_mul_f32 v[120:121], v[120:121], v[124:125]
	v_pk_mul_f32 v[124:125], v[126:127], v[184:185] op_sel_hi:[1,0]
	v_pk_mul_f32 v[80:81], v[80:81], v[146:147] op_sel_hi:[1,0]
	v_mul_f32_e32 v126, 0xbfb8aa3b, v124
	v_mul_f32_e32 v127, 0xbfb8aa3b, v125
	v_exp_f32_e32 v126, v126
	v_exp_f32_e32 v127, v127
	v_pk_mul_f32 v[82:83], v[82:83], v[146:147] op_sel_hi:[1,0]
	v_pk_mul_f32 v[76:77], v[76:77], v[144:145] op_sel_hi:[1,0]
	v_add_f32_e32 v126, 1.0, v126
	v_add_f32_e32 v127, 1.0, v127
	v_rcp_f32_e32 v126, v126
	v_rcp_f32_e32 v127, v127
	v_pk_mul_f32 v[72:73], v[72:73], v[144:145] op_sel_hi:[1,0]
	v_pk_mul_f32 v[74:75], v[74:75], v[144:145] op_sel_hi:[1,0]
	v_pk_mul_f32 v[68:69], v[68:69], v[144:145] op_sel_hi:[1,0]
	v_pk_mul_f32 v[124:125], v[124:125], v[126:127]
	v_pk_mul_f32 v[64:65], v[64:65], v[144:145] op_sel_hi:[1,0]
	v_pk_mul_f32 v[122:123], v[122:123], v[124:125]
	v_mul_f32_e32 v124, 0xbfb8aa3b, v116
	v_mul_f32_e32 v125, 0xbfb8aa3b, v117
	v_exp_f32_e32 v124, v124
	v_exp_f32_e32 v125, v125
	v_pk_mul_f32 v[66:67], v[66:67], v[144:145] op_sel_hi:[1,0]
	v_pk_mul_f32 v[60:61], v[60:61], v[138:139] op_sel_hi:[1,0]
	v_add_f32_e32 v124, 1.0, v124
	v_add_f32_e32 v125, 1.0, v125
	v_rcp_f32_e32 v124, v124
	v_rcp_f32_e32 v125, v125
	v_pk_mul_f32 v[56:57], v[56:57], v[138:139] op_sel_hi:[1,0]
	v_pk_mul_f32 v[58:59], v[58:59], v[138:139] op_sel_hi:[1,0]
	v_pk_mul_f32 v[52:53], v[52:53], v[138:139] op_sel_hi:[1,0]
	v_pk_mul_f32 v[116:117], v[116:117], v[124:125]
	v_pk_mul_f32 v[48:49], v[48:49], v[138:139] op_sel_hi:[1,0]
	v_pk_mul_f32 v[112:113], v[112:113], v[116:117]
	v_pk_mul_f32 v[116:117], v[118:119], v[184:185] op_sel_hi:[1,0]
	v_pk_mul_f32 v[50:51], v[50:51], v[138:139] op_sel_hi:[1,0]
	v_mul_f32_e32 v118, 0xbfb8aa3b, v116
	v_mul_f32_e32 v119, 0xbfb8aa3b, v117
	v_exp_f32_e32 v118, v118
	v_exp_f32_e32 v119, v119
	v_pk_mul_f32 v[44:45], v[44:45], v[136:137] op_sel_hi:[1,0]
	v_pk_mul_f32 v[40:41], v[40:41], v[136:137] op_sel_hi:[1,0]
	v_add_f32_e32 v118, 1.0, v118
	v_add_f32_e32 v119, 1.0, v119
	v_rcp_f32_e32 v118, v118
	v_rcp_f32_e32 v119, v119
	v_pk_mul_f32 v[42:43], v[42:43], v[136:137] op_sel_hi:[1,0]
	v_pk_mul_f32 v[36:37], v[36:37], v[136:137] op_sel_hi:[1,0]
	v_pk_mul_f32 v[32:33], v[32:33], v[136:137] op_sel_hi:[1,0]
	v_pk_mul_f32 v[116:117], v[116:117], v[118:119]
	v_cvt_pk_bf16_f32 v118, v112, v113
	v_pk_mul_f32 v[114:115], v[114:115], v[116:117]
	v_mov_b64_e32 v[112:113], s[12:13]
	v_cvt_pk_bf16_f32 v116, v120, v121
	v_cvt_pk_bf16_f32 v119, v114, v115
	v_mad_i64_i32 v[120:121], s[8:9], v178, s3, v[112:113]
	v_lshlrev_b64 v[114:115], 1, v[180:181]
	v_cvt_pk_bf16_f32 v117, v122, v123
	v_lshl_add_u64 v[120:121], v[120:121], 0, v[114:115]
	global_store_dwordx4 v[120:121], v[116:119], off
	v_pk_mul_f32 v[34:35], v[34:35], v[136:137] op_sel_hi:[1,0]
	v_pk_mul_f32 v[28:29], v[28:29], v[130:131] op_sel_hi:[1,0]
	v_mul_f32_e32 v116, 0xbfb8aa3b, v108
	v_mul_f32_e32 v117, 0xbfb8aa3b, v109
	v_exp_f32_e32 v116, v116
	v_exp_f32_e32 v117, v117
	v_pk_mul_f32 v[24:25], v[24:25], v[130:131] op_sel_hi:[1,0]
	v_pk_mul_f32 v[26:27], v[26:27], v[130:131] op_sel_hi:[1,0]
	v_add_f32_e32 v116, 1.0, v116
	v_add_f32_e32 v117, 1.0, v117
	v_rcp_f32_e32 v116, v116
	v_rcp_f32_e32 v117, v117
	v_pk_mul_f32 v[20:21], v[20:21], v[130:131] op_sel_hi:[1,0]
	v_pk_mul_f32 v[16:17], v[16:17], v[130:131] op_sel_hi:[1,0]
	v_pk_mul_f32 v[18:19], v[18:19], v[130:131] op_sel_hi:[1,0]
	v_pk_mul_f32 v[108:109], v[108:109], v[116:117]
	v_pk_mul_f32 v[12:13], v[12:13], v[128:129] op_sel_hi:[1,0]
	v_pk_mul_f32 v[104:105], v[104:105], v[108:109]
	v_pk_mul_f32 v[108:109], v[110:111], v[182:183] op_sel_hi:[1,0]
	v_pk_mul_f32 v[8:9], v[8:9], v[128:129] op_sel_hi:[1,0]
	v_mul_f32_e32 v110, 0xbfb8aa3b, v108
	v_mul_f32_e32 v111, 0xbfb8aa3b, v109
	v_exp_f32_e32 v110, v110
	v_exp_f32_e32 v111, v111
	v_pk_mul_f32 v[10:11], v[10:11], v[128:129] op_sel_hi:[1,0]
	v_pk_mul_f32 v[4:5], v[4:5], v[128:129] op_sel_hi:[1,0]
	v_add_f32_e32 v110, 1.0, v110
	v_add_f32_e32 v111, 1.0, v111
	v_rcp_f32_e32 v110, v110
	v_rcp_f32_e32 v111, v111
	v_pk_mul_f32 v[0:1], v[0:1], v[128:129] op_sel_hi:[1,0]
	v_pk_mul_f32 v[2:3], v[2:3], v[128:129] op_sel_hi:[1,0]
	s_andn2_b64 vcc, exec, s[6:7]
	v_pk_mul_f32 v[108:109], v[108:109], v[110:111]
	s_nop 0
	v_pk_mul_f32 v[106:107], v[106:107], v[108:109]
	v_mul_f32_e32 v108, 0xbfb8aa3b, v100
	v_mul_f32_e32 v109, 0xbfb8aa3b, v101
	v_exp_f32_e32 v108, v108
	v_exp_f32_e32 v109, v109
	v_add_f32_e32 v108, 1.0, v108
	v_add_f32_e32 v109, 1.0, v109
	v_rcp_f32_e32 v108, v108
	v_rcp_f32_e32 v109, v109
	s_nop 0
	v_pk_mul_f32 v[100:101], v[100:101], v[108:109]
	s_nop 0
	v_pk_mul_f32 v[100:101], v[96:97], v[100:101]
	v_pk_mul_f32 v[96:97], v[102:103], v[182:183] op_sel_hi:[1,0]
	s_nop 0
	v_mul_f32_e32 v102, 0xbfb8aa3b, v96
	v_mul_f32_e32 v103, 0xbfb8aa3b, v97
	v_exp_f32_e32 v102, v102
	v_exp_f32_e32 v103, v103
	v_add_f32_e32 v102, 1.0, v102
	v_add_f32_e32 v103, 1.0, v103
	v_rcp_f32_e32 v102, v102
	v_rcp_f32_e32 v103, v103
	s_nop 0
	v_pk_mul_f32 v[96:97], v[96:97], v[102:103]
	s_nop 0
	v_pk_mul_f32 v[102:103], v[98:99], v[96:97]
	v_cvt_pk_bf16_f32 v98, v100, v101
	v_mad_i64_i32 v[100:101], s[8:9], v176, s3, v[112:113]
	v_cvt_pk_bf16_f32 v96, v104, v105
	v_cvt_pk_bf16_f32 v97, v106, v107
	v_cvt_pk_bf16_f32 v99, v102, v103
	v_lshl_add_u64 v[100:101], v[100:101], 0, v[114:115]
	global_store_dwordx4 v[100:101], v[96:99], off
	s_nop 1
	v_mul_f32_e32 v96, 0xbfb8aa3b, v92
	v_mul_f32_e32 v97, 0xbfb8aa3b, v93
	v_exp_f32_e32 v96, v96
	v_exp_f32_e32 v97, v97
	v_add_f32_e32 v96, 1.0, v96
	v_add_f32_e32 v97, 1.0, v97
	v_rcp_f32_e32 v96, v96
	v_rcp_f32_e32 v97, v97
	s_nop 0
	v_pk_mul_f32 v[92:93], v[92:93], v[96:97]
	s_nop 0
	v_pk_mul_f32 v[88:89], v[88:89], v[92:93]
	v_pk_mul_f32 v[92:93], v[94:95], v[146:147] op_sel_hi:[1,0]
	s_nop 0
	v_mul_f32_e32 v94, 0xbfb8aa3b, v92
	v_mul_f32_e32 v95, 0xbfb8aa3b, v93
	v_exp_f32_e32 v94, v94
	v_exp_f32_e32 v95, v95
	v_add_f32_e32 v94, 1.0, v94
	v_add_f32_e32 v95, 1.0, v95
	v_rcp_f32_e32 v94, v94
	v_rcp_f32_e32 v95, v95
	s_nop 0
	v_pk_mul_f32 v[92:93], v[92:93], v[94:95]
	s_nop 0
	v_pk_mul_f32 v[90:91], v[90:91], v[92:93]
	v_mul_f32_e32 v92, 0xbfb8aa3b, v84
	v_mul_f32_e32 v93, 0xbfb8aa3b, v85
	v_exp_f32_e32 v92, v92
	v_exp_f32_e32 v93, v93
	v_add_f32_e32 v92, 1.0, v92
	v_add_f32_e32 v93, 1.0, v93
	v_rcp_f32_e32 v92, v92
	v_rcp_f32_e32 v93, v93
	s_nop 0
	v_pk_mul_f32 v[84:85], v[84:85], v[92:93]
	s_nop 0
	v_pk_mul_f32 v[84:85], v[80:81], v[84:85]
	v_pk_mul_f32 v[80:81], v[86:87], v[146:147] op_sel_hi:[1,0]
	s_nop 0
	v_mul_f32_e32 v86, 0xbfb8aa3b, v80
	v_mul_f32_e32 v87, 0xbfb8aa3b, v81
	v_exp_f32_e32 v86, v86
	v_exp_f32_e32 v87, v87
	v_add_f32_e32 v86, 1.0, v86
	v_add_f32_e32 v87, 1.0, v87
	v_rcp_f32_e32 v86, v86
	v_rcp_f32_e32 v87, v87
	s_nop 0
	v_pk_mul_f32 v[80:81], v[80:81], v[86:87]
	s_nop 0
	v_pk_mul_f32 v[86:87], v[82:83], v[80:81]
	v_cvt_pk_bf16_f32 v82, v84, v85
	v_mad_i64_i32 v[84:85], s[8:9], v174, s3, v[112:113]
	v_cvt_pk_bf16_f32 v80, v88, v89
	v_cvt_pk_bf16_f32 v81, v90, v91
	v_cvt_pk_bf16_f32 v83, v86, v87
	v_lshl_add_u64 v[84:85], v[84:85], 0, v[114:115]
	global_store_dwordx4 v[84:85], v[80:83], off
	s_nop 1
	v_mul_f32_e32 v80, 0xbfb8aa3b, v76
	v_mul_f32_e32 v81, 0xbfb8aa3b, v77
	v_exp_f32_e32 v80, v80
	v_exp_f32_e32 v81, v81
	v_add_f32_e32 v80, 1.0, v80
	v_add_f32_e32 v81, 1.0, v81
	v_rcp_f32_e32 v80, v80
	v_rcp_f32_e32 v81, v81
	s_nop 0
	v_pk_mul_f32 v[76:77], v[76:77], v[80:81]
	s_nop 0
	v_pk_mul_f32 v[72:73], v[72:73], v[76:77]
	v_pk_mul_f32 v[76:77], v[78:79], v[144:145] op_sel_hi:[1,0]
	s_nop 0
	v_mul_f32_e32 v78, 0xbfb8aa3b, v76
	v_mul_f32_e32 v79, 0xbfb8aa3b, v77
	v_exp_f32_e32 v78, v78
	v_exp_f32_e32 v79, v79
	v_add_f32_e32 v78, 1.0, v78
	v_add_f32_e32 v79, 1.0, v79
	v_rcp_f32_e32 v78, v78
	v_rcp_f32_e32 v79, v79
	s_nop 0
	v_pk_mul_f32 v[76:77], v[76:77], v[78:79]
	s_nop 0
	v_pk_mul_f32 v[74:75], v[74:75], v[76:77]
	v_mul_f32_e32 v76, 0xbfb8aa3b, v68
	v_mul_f32_e32 v77, 0xbfb8aa3b, v69
	v_exp_f32_e32 v76, v76
	v_exp_f32_e32 v77, v77
	v_add_f32_e32 v76, 1.0, v76
	v_add_f32_e32 v77, 1.0, v77
	v_rcp_f32_e32 v76, v76
	v_rcp_f32_e32 v77, v77
	s_nop 0
	v_pk_mul_f32 v[68:69], v[68:69], v[76:77]
	s_nop 0
	v_pk_mul_f32 v[68:69], v[64:65], v[68:69]
	v_pk_mul_f32 v[64:65], v[70:71], v[144:145] op_sel_hi:[1,0]
	s_nop 0
	v_mul_f32_e32 v70, 0xbfb8aa3b, v64
	v_mul_f32_e32 v71, 0xbfb8aa3b, v65
	v_exp_f32_e32 v70, v70
	v_exp_f32_e32 v71, v71
	v_add_f32_e32 v70, 1.0, v70
	v_add_f32_e32 v71, 1.0, v71
	v_rcp_f32_e32 v70, v70
	v_rcp_f32_e32 v71, v71
	s_nop 0
	v_pk_mul_f32 v[64:65], v[64:65], v[70:71]
	s_nop 0
	v_pk_mul_f32 v[70:71], v[66:67], v[64:65]
	v_cvt_pk_bf16_f32 v66, v68, v69
	v_mad_i64_i32 v[68:69], s[8:9], v172, s3, v[112:113]
	v_cvt_pk_bf16_f32 v64, v72, v73
	v_cvt_pk_bf16_f32 v65, v74, v75
	v_cvt_pk_bf16_f32 v67, v70, v71
	v_lshl_add_u64 v[68:69], v[68:69], 0, v[114:115]
	global_store_dwordx4 v[68:69], v[64:67], off
	s_nop 1
	v_mul_f32_e32 v64, 0xbfb8aa3b, v60
	v_mul_f32_e32 v65, 0xbfb8aa3b, v61
	v_exp_f32_e32 v64, v64
	v_exp_f32_e32 v65, v65
	v_add_f32_e32 v64, 1.0, v64
	v_add_f32_e32 v65, 1.0, v65
	v_rcp_f32_e32 v64, v64
	v_rcp_f32_e32 v65, v65
	s_nop 0
	v_pk_mul_f32 v[60:61], v[60:61], v[64:65]
	s_nop 0
	v_pk_mul_f32 v[56:57], v[56:57], v[60:61]
	v_pk_mul_f32 v[60:61], v[62:63], v[138:139] op_sel_hi:[1,0]
	s_nop 0
	v_mul_f32_e32 v62, 0xbfb8aa3b, v60
	v_mul_f32_e32 v63, 0xbfb8aa3b, v61
	v_exp_f32_e32 v62, v62
	v_exp_f32_e32 v63, v63
	v_add_f32_e32 v62, 1.0, v62
	v_add_f32_e32 v63, 1.0, v63
	v_rcp_f32_e32 v62, v62
	v_rcp_f32_e32 v63, v63
	s_nop 0
	v_pk_mul_f32 v[60:61], v[60:61], v[62:63]
	s_nop 0
	v_pk_mul_f32 v[58:59], v[58:59], v[60:61]
	v_mul_f32_e32 v60, 0xbfb8aa3b, v52
	v_mul_f32_e32 v61, 0xbfb8aa3b, v53
	v_exp_f32_e32 v60, v60
	v_exp_f32_e32 v61, v61
	v_add_f32_e32 v60, 1.0, v60
	v_add_f32_e32 v61, 1.0, v61
	v_rcp_f32_e32 v60, v60
	v_rcp_f32_e32 v61, v61
	s_nop 0
	v_pk_mul_f32 v[52:53], v[52:53], v[60:61]
	s_nop 0
	v_pk_mul_f32 v[52:53], v[48:49], v[52:53]
	v_pk_mul_f32 v[48:49], v[54:55], v[138:139] op_sel_hi:[1,0]
	s_nop 0
	v_mul_f32_e32 v54, 0xbfb8aa3b, v48
	v_mul_f32_e32 v55, 0xbfb8aa3b, v49
	v_exp_f32_e32 v54, v54
	v_exp_f32_e32 v55, v55
	v_add_f32_e32 v54, 1.0, v54
	v_add_f32_e32 v55, 1.0, v55
	v_rcp_f32_e32 v54, v54
	v_rcp_f32_e32 v55, v55
	s_nop 0
	v_pk_mul_f32 v[48:49], v[48:49], v[54:55]
	s_nop 0
	v_pk_mul_f32 v[54:55], v[50:51], v[48:49]
	v_cvt_pk_bf16_f32 v50, v52, v53
	v_mad_i64_i32 v[52:53], s[8:9], v170, s3, v[112:113]
	v_cvt_pk_bf16_f32 v48, v56, v57
	v_cvt_pk_bf16_f32 v49, v58, v59
	v_cvt_pk_bf16_f32 v51, v54, v55
	v_lshl_add_u64 v[52:53], v[52:53], 0, v[114:115]
	global_store_dwordx4 v[52:53], v[48:51], off
	s_nop 1
	v_mul_f32_e32 v48, 0xbfb8aa3b, v44
	v_mul_f32_e32 v49, 0xbfb8aa3b, v45
	v_exp_f32_e32 v48, v48
	v_exp_f32_e32 v49, v49
	v_add_f32_e32 v48, 1.0, v48
	v_add_f32_e32 v49, 1.0, v49
	v_rcp_f32_e32 v48, v48
	v_rcp_f32_e32 v49, v49
	s_nop 0
	v_pk_mul_f32 v[44:45], v[44:45], v[48:49]
	s_nop 0
	v_pk_mul_f32 v[40:41], v[40:41], v[44:45]
	v_pk_mul_f32 v[44:45], v[46:47], v[136:137] op_sel_hi:[1,0]
	s_nop 0
	v_mul_f32_e32 v46, 0xbfb8aa3b, v44
	v_mul_f32_e32 v47, 0xbfb8aa3b, v45
	v_exp_f32_e32 v46, v46
	v_exp_f32_e32 v47, v47
	v_add_f32_e32 v46, 1.0, v46
	v_add_f32_e32 v47, 1.0, v47
	v_rcp_f32_e32 v46, v46
	v_rcp_f32_e32 v47, v47
	s_nop 0
	v_pk_mul_f32 v[44:45], v[44:45], v[46:47]
	s_nop 0
	v_pk_mul_f32 v[42:43], v[42:43], v[44:45]
	v_mul_f32_e32 v44, 0xbfb8aa3b, v36
	v_mul_f32_e32 v45, 0xbfb8aa3b, v37
	v_exp_f32_e32 v44, v44
	v_exp_f32_e32 v45, v45
	v_add_f32_e32 v44, 1.0, v44
	v_add_f32_e32 v45, 1.0, v45
	v_rcp_f32_e32 v44, v44
	v_rcp_f32_e32 v45, v45
	s_nop 0
	v_pk_mul_f32 v[36:37], v[36:37], v[44:45]
	s_nop 0
	v_pk_mul_f32 v[36:37], v[32:33], v[36:37]
	v_pk_mul_f32 v[32:33], v[38:39], v[136:137] op_sel_hi:[1,0]
	s_nop 0
	v_mul_f32_e32 v38, 0xbfb8aa3b, v32
	v_mul_f32_e32 v39, 0xbfb8aa3b, v33
	v_exp_f32_e32 v38, v38
	v_exp_f32_e32 v39, v39
	v_add_f32_e32 v38, 1.0, v38
	v_add_f32_e32 v39, 1.0, v39
	v_rcp_f32_e32 v38, v38
	v_rcp_f32_e32 v39, v39
	s_nop 0
	v_pk_mul_f32 v[32:33], v[32:33], v[38:39]
	s_nop 0
	v_pk_mul_f32 v[38:39], v[34:35], v[32:33]
	v_cvt_pk_bf16_f32 v34, v36, v37
	v_mad_i64_i32 v[36:37], s[8:9], v168, s3, v[112:113]
	v_cvt_pk_bf16_f32 v32, v40, v41
	v_cvt_pk_bf16_f32 v33, v42, v43
	v_cvt_pk_bf16_f32 v35, v38, v39
	v_lshl_add_u64 v[36:37], v[36:37], 0, v[114:115]
	global_store_dwordx4 v[36:37], v[32:35], off
	s_nop 1
	v_mul_f32_e32 v32, 0xbfb8aa3b, v28
	v_mul_f32_e32 v33, 0xbfb8aa3b, v29
	v_exp_f32_e32 v32, v32
	v_exp_f32_e32 v33, v33
	v_add_f32_e32 v32, 1.0, v32
	v_add_f32_e32 v33, 1.0, v33
	v_rcp_f32_e32 v32, v32
	v_rcp_f32_e32 v33, v33
	s_nop 0
	v_pk_mul_f32 v[28:29], v[28:29], v[32:33]
	s_nop 0
	v_pk_mul_f32 v[24:25], v[24:25], v[28:29]
	v_pk_mul_f32 v[28:29], v[30:31], v[130:131] op_sel_hi:[1,0]
	s_nop 0
	v_mul_f32_e32 v30, 0xbfb8aa3b, v28
	v_mul_f32_e32 v31, 0xbfb8aa3b, v29
	v_exp_f32_e32 v30, v30
	v_exp_f32_e32 v31, v31
	v_add_f32_e32 v30, 1.0, v30
	v_add_f32_e32 v31, 1.0, v31
	v_rcp_f32_e32 v30, v30
	v_rcp_f32_e32 v31, v31
	s_nop 0
	v_pk_mul_f32 v[28:29], v[28:29], v[30:31]
	s_nop 0
	v_pk_mul_f32 v[26:27], v[26:27], v[28:29]
	v_mul_f32_e32 v28, 0xbfb8aa3b, v20
	v_mul_f32_e32 v29, 0xbfb8aa3b, v21
	v_exp_f32_e32 v28, v28
	v_exp_f32_e32 v29, v29
	v_add_f32_e32 v28, 1.0, v28
	v_add_f32_e32 v29, 1.0, v29
	v_rcp_f32_e32 v28, v28
	v_rcp_f32_e32 v29, v29
	s_nop 0
	v_pk_mul_f32 v[20:21], v[20:21], v[28:29]
	s_nop 0
	v_pk_mul_f32 v[20:21], v[16:17], v[20:21]
	v_pk_mul_f32 v[16:17], v[22:23], v[130:131] op_sel_hi:[1,0]
	s_nop 0
	v_mul_f32_e32 v22, 0xbfb8aa3b, v16
	v_mul_f32_e32 v23, 0xbfb8aa3b, v17
	v_exp_f32_e32 v22, v22
	v_exp_f32_e32 v23, v23
	v_add_f32_e32 v22, 1.0, v22
	v_add_f32_e32 v23, 1.0, v23
	v_rcp_f32_e32 v22, v22
	v_rcp_f32_e32 v23, v23
	s_nop 0
	v_pk_mul_f32 v[16:17], v[16:17], v[22:23]
	s_nop 0
	v_pk_mul_f32 v[22:23], v[18:19], v[16:17]
	v_cvt_pk_bf16_f32 v18, v20, v21
	v_mad_i64_i32 v[20:21], s[8:9], v166, s3, v[112:113]
	v_cvt_pk_bf16_f32 v16, v24, v25
	v_cvt_pk_bf16_f32 v17, v26, v27
	v_cvt_pk_bf16_f32 v19, v22, v23
	v_lshl_add_u64 v[20:21], v[20:21], 0, v[114:115]
	global_store_dwordx4 v[20:21], v[16:19], off
	s_nop 1
	v_mul_f32_e32 v16, 0xbfb8aa3b, v12
	v_mul_f32_e32 v17, 0xbfb8aa3b, v13
	v_exp_f32_e32 v16, v16
	v_exp_f32_e32 v17, v17
	v_add_f32_e32 v16, 1.0, v16
	v_add_f32_e32 v17, 1.0, v17
	v_rcp_f32_e32 v16, v16
	v_rcp_f32_e32 v17, v17
	s_nop 0
	v_pk_mul_f32 v[12:13], v[12:13], v[16:17]
	s_nop 0
	v_pk_mul_f32 v[8:9], v[8:9], v[12:13]
	v_pk_mul_f32 v[12:13], v[14:15], v[128:129] op_sel_hi:[1,0]
	s_nop 0
	v_mul_f32_e32 v14, 0xbfb8aa3b, v12
	v_mul_f32_e32 v15, 0xbfb8aa3b, v13
	v_exp_f32_e32 v14, v14
	v_exp_f32_e32 v15, v15
	v_add_f32_e32 v14, 1.0, v14
	v_add_f32_e32 v15, 1.0, v15
	v_rcp_f32_e32 v14, v14
	v_rcp_f32_e32 v15, v15
	s_nop 0
	v_pk_mul_f32 v[12:13], v[12:13], v[14:15]
	s_nop 0
	v_pk_mul_f32 v[10:11], v[10:11], v[12:13]
	v_mul_f32_e32 v12, 0xbfb8aa3b, v4
	v_mul_f32_e32 v13, 0xbfb8aa3b, v5
	v_exp_f32_e32 v12, v12
	v_exp_f32_e32 v13, v13
	v_add_f32_e32 v12, 1.0, v12
	v_add_f32_e32 v13, 1.0, v13
	v_rcp_f32_e32 v12, v12
	v_rcp_f32_e32 v13, v13
	s_nop 0
	v_pk_mul_f32 v[4:5], v[4:5], v[12:13]
	s_nop 0
	v_pk_mul_f32 v[4:5], v[0:1], v[4:5]
	v_pk_mul_f32 v[0:1], v[6:7], v[128:129] op_sel_hi:[1,0]
	s_nop 0
	v_mul_f32_e32 v6, 0xbfb8aa3b, v0
	v_mul_f32_e32 v7, 0xbfb8aa3b, v1
	v_exp_f32_e32 v6, v6
	v_exp_f32_e32 v7, v7
	v_add_f32_e32 v6, 1.0, v6
	v_add_f32_e32 v7, 1.0, v7
	v_rcp_f32_e32 v6, v6
	v_rcp_f32_e32 v7, v7
	s_nop 0
	v_pk_mul_f32 v[0:1], v[0:1], v[6:7]
	s_nop 0
	v_pk_mul_f32 v[6:7], v[2:3], v[0:1]
	v_cvt_pk_bf16_f32 v2, v4, v5
	v_mad_i64_i32 v[4:5], s[8:9], v164, s3, v[112:113]
	v_cvt_pk_bf16_f32 v0, v8, v9
	v_cvt_pk_bf16_f32 v1, v10, v11
	v_cvt_pk_bf16_f32 v3, v6, v7
	v_lshl_add_u64 v[4:5], v[4:5], 0, v[114:115]
	s_mov_b64 s[8:9], -1
	global_store_dwordx4 v[4:5], v[0:3], off
	s_cbranch_vccnz .LBB0_931
	s_andn2_b64 vcc, exec, s[10:11]
	s_cbranch_vccnz .LBB0_930
	s_barrier
	s_branch .LBB0_930
